# on top: GEMM K-loop heads aligned to 64 bytes
# baseline (speedup 1.0000x reference)
; template <class Epi, class Sched, bool ALIGN_EPI = false, bool SP2 = false>
; __device__ __forceinline__ void gemm_phase(PG8_LAS unsigned char* lds, const Gemm g, const Sched& S, const Epi& E) {
;     ...
;         const bool has_next = S.next(ui + 1, nxt);
;         const char* nA = has_next ? (const char*)g.A + (size_t)nxt.pm * tstep : cA; const char* nB = has_next ? (const char*)g.Bt + (size_t)nxt.pn * tstep : cB;
;         for (int t = 0; t < nt; t += 2) {
;             const bool last = (t == nt - 2);
;             const char* a1 = cA + (size_t)(t + 1) * kstep;
;             const char* a2 = last ? nA : cA + (size_t)(t + 2) * kstep; const char* b2 = last ? nB : cB + (size_t)(t + 2) * kstep;
;             const char* a3 = a2 + kstep; const char* b3 = b2 + kstep;
.LBB0_131:
	s_ashr_i32 s73, s72, 31
	s_lshl_b64 s[38:39], s[72:73], 19
	s_add_u32 s76, s4, s38
	s_addc_u32 s77, s5, s39
	s_and_b64 s[38:39], s[42:43], exec
	s_cselect_b32 s33, s77, s47
	s_cselect_b32 s73, s76, s46
	s_ashr_i32 s75, s74, 31
	s_lshl_b64 s[38:39], s[74:75], 19
	s_add_u32 s78, s58, s38
	s_addc_u32 s79, s90, s39
	s_and_b64 s[38:39], s[42:43], exec
	s_cselect_b32 s75, s79, s45
	s_cselect_b32 s82, s78, s44
	s_add_u32 s46, s46, 0x40080
	s_addc_u32 s47, s47, 0
	s_add_u32 s83, s44, 0x100
	s_addc_u32 s84, s45, 0
	s_mov_b32 s85, -2
	.p2align 6

; template <class Epi, class Sched, bool ALIGN_EPI = false, bool SP2 = false>
; __device__ __forceinline__ void gemm_phase(PG8_LAS unsigned char* lds, const Gemm g, const Sched& S, const Epi& E) {
;     ...
;         const bool has_next = S.next(ui + 1, nxt);
;         const char* nA = has_next ? (const char*)g.A + (size_t)nxt.pm * tstep : cA; const char* nB = has_next ? (const char*)g.Bt + (size_t)nxt.pn * tstep : cB;
;         for (int t = 0; t < nt; t += 2) {
;             const bool last = (t == nt - 2);
;             const char* a1 = cA + (size_t)(t + 1) * kstep;
;             const char* a2 = last ? nA : cA + (size_t)(t + 2) * kstep; const char* b2 = last ? nB : cB + (size_t)(t + 2) * kstep;
;             const char* a3 = a2 + kstep; const char* b3 = b2 + kstep;
.LBB0_219:
	s_ashr_i32 s47, s46, 31
	s_lshl_b64 s[38:39], s[46:47], 19
	s_add_u32 s50, s4, s38
	s_addc_u32 s51, s5, s39
	s_and_b64 s[38:39], s[42:43], exec
	s_cselect_b32 s47, s51, s61
	s_cselect_b32 s78, s50, s60
	s_ashr_i32 s49, s48, 31
	s_lshl_b64 s[38:39], s[48:49], 19
	s_add_u32 s52, s6, s38
	s_addc_u32 s53, s7, s39
	s_and_b64 s[38:39], s[42:43], exec
	s_cselect_b32 s49, s53, s57
	s_cselect_b32 s79, s52, s56
	s_add_u32 s60, s60, 0x40080
	s_addc_u32 s61, s61, 0
	s_add_u32 s80, s56, 0x100
	s_addc_u32 s81, s57, 0
	s_mov_b32 s82, -2
	.p2align 6

; template <class Epi, class Sched, bool ALIGN_EPI = false, bool SP2 = false>
; __device__ __forceinline__ void gemm_phase(PG8_LAS unsigned char* lds, const Gemm g, const Sched& S, const Epi& E) {
;     ...
;             const char* a1 = cA + (size_t)(t + 1) * kstep;
;             const char* a2 = last ? nA : cA + (size_t)(t + 2) * kstep; const char* b2 = last ? nB : cB + (size_t)(t + 2) * kstep;
;             const char* a3 = a2 + kstep; const char* b3 = b2 + kstep;
.LBB0_273:
	s_add_u32 s48, s48, 0x80
	s_addc_u32 s49, s49, 0
	s_add_u32 s50, s46, 0x100
	s_addc_u32 s51, s47, 0
	s_mov_b32 s46, 0
	.p2align 6

; template <class Epi, class Sched, bool ALIGN_EPI = false, bool SP2 = false>
; __device__ __forceinline__ void gemm_phase(PG8_LAS unsigned char* lds, const Gemm g, const Sched& S, const Epi& E) {
;     ...
;         const bool has_next = S.next(ui + 1, nxt);
;         const char* nA = has_next ? (const char*)g.A + (size_t)nxt.pm * tstep : cA; const char* nB = has_next ? (const char*)g.Bt + (size_t)nxt.pn * tstep : cB;
;         for (int t = 0; t < nt; t += 2) {
;             const bool last = (t == nt - 2);
;             const char* a1 = cA + (size_t)(t + 1) * kstep;
;             const char* a2 = last ? nA : cA + (size_t)(t + 2) * kstep; const char* b2 = last ? nB : cB + (size_t)(t + 2) * kstep;
;             const char* a3 = a2 + kstep; const char* b3 = b2 + kstep;
.LBB0_407:
	s_ashr_i32 s21, s20, 31
	s_lshl_b64 s[10:11], s[20:21], 19
	s_add_u32 s10, s4, s10
	s_addc_u32 s11, s5, s11
	s_and_b64 s[60:61], s[44:45], exec
	s_cselect_b32 s21, s11, s49
	s_cselect_b32 s27, s10, s48
	s_ashr_i32 s53, s52, 31
	s_lshl_b64 s[60:61], s[52:53], 19
	s_add_u32 s60, s58, s60
	s_addc_u32 s61, s74, s61
	s_and_b64 s[72:73], s[44:45], exec
	s_cselect_b32 s29, s61, s47
	s_cselect_b32 s33, s60, s46
	s_add_u32 s48, s48, 0x40080
	s_addc_u32 s49, s49, 0
	s_add_u32 s53, s46, 0x100
	s_addc_u32 s69, s47, 0
	s_mov_b32 s84, -2
	.p2align 6
